# v11 + attention-loop bf16 packs via v_cvt_pk_bf16_f32 (41 sites) + P5 epilogue second-half residual loads issued with the first half's
# speedup vs baseline: 1.0210x; 1.0029x over previous
; #define GAS __attribute__((address_space(1)))
; __device__ __forceinline__ unsigned pk2(float lo, float hi) { return f2bf(lo) | (f2bf(hi) << 16); }
; __device__ __forceinline__ void attn_conv_unit(LAS unsigned char* lds, int unit, const bf16* Z, bf16* Y, float* RA,
;                                                const float* qg, const float* kg, const float* sinks, const float* convw) {
;     ...
;             const float inv = 1.0f / l;
;             float sq = 0.f;
; #pragma unroll
;             for (int dt = 0; dt < 2; ++dt)
; #pragma unroll
;                 for (int r = 0; r < 16; ++r) { o[dt][r] *= inv; sq += o[dt][r] * o[dt][r]; }
;             sq += __shfl_xor(sq, 32);
;             if (hi == 0) SS[(32 * j + r32) * 8 + h] = sq;
;             bf16* yrow = Y + tokq * D + h * 64 + 4 * hi;
; #pragma unroll
;             for (int dt = 0; dt < 2; ++dt)
; #pragma unroll
;                 for (int g = 0; g < 4; ++g) { v2u w; w.x = pk2(o[dt][4 * g + 0], o[dt][4 * g + 1]); w.y = pk2(o[dt][4 * g + 2], o[dt][4 * g + 3]);
;                     *(GAS v2u*)(yrow + 32 * dt + 8 * g) = w; }
.LBB0_438:
	s_or_b64 exec, exec, s[48:49]
	s_waitcnt lgkmcnt(0)
	v_cvt_pk_bf16_f32 v9, v41, v43
	v_cvt_pk_bf16_f32 v8, v40, v42
	global_store_dwordx2 v[160:161], v[8:9], off offset:-64
	v_cvt_pk_bf16_f32 v9, v37, v39
	v_cvt_pk_bf16_f32 v8, v36, v38
	global_store_dwordx2 v[160:161], v[8:9], off offset:-48
	v_cvt_pk_bf16_f32 v9, v33, v35
	v_cvt_pk_bf16_f32 v8, v32, v34
	global_store_dwordx2 v[160:161], v[8:9], off offset:-32
	v_cvt_pk_bf16_f32 v9, v25, v27
	v_cvt_pk_bf16_f32 v8, v24, v26
	global_store_dwordx2 v[160:161], v[8:9], off offset:-16
	v_cvt_pk_bf16_f32 v9, v21, v23
	v_cvt_pk_bf16_f32 v8, v20, v22
	global_store_dwordx2 v[160:161], v[8:9], off
	v_cvt_pk_bf16_f32 v9, v17, v19
	v_cvt_pk_bf16_f32 v8, v16, v18
	global_store_dwordx2 v[160:161], v[8:9], off offset:16
	v_and_b32_sdwa v8, v5, v181 dst_sel:DWORD dst_unused:UNUSED_PAD src0_sel:WORD_1 src1_sel:DWORD
	v_and_b32_sdwa v9, v4, v181 dst_sel:DWORD dst_unused:UNUSED_PAD src0_sel:WORD_1 src1_sel:DWORD
	v_add3_u32 v4, v4, v9, s98
	v_add3_u32 v5, v5, v8, s98
	v_and_b32_sdwa v8, v7, v181 dst_sel:DWORD dst_unused:UNUSED_PAD src0_sel:WORD_1 src1_sel:DWORD
	v_and_b32_sdwa v9, v6, v181 dst_sel:DWORD dst_unused:UNUSED_PAD src0_sel:WORD_1 src1_sel:DWORD
	v_add3_u32 v7, v7, v8, s98
	v_add3_u32 v6, v6, v9, s98
	v_and_b32_e32 v7, 0xffff0000, v7
	v_and_b32_e32 v6, 0xffff0000, v6
	v_or_b32_sdwa v5, v7, v5 dst_sel:DWORD dst_unused:UNUSED_PAD src0_sel:DWORD src1_sel:WORD_1
	v_or_b32_sdwa v4, v6, v4 dst_sel:DWORD dst_unused:UNUSED_PAD src0_sel:DWORD src1_sel:WORD_1
	global_store_dwordx2 v[160:161], v[4:5], off offset:32
	v_and_b32_sdwa v4, v1, v181 dst_sel:DWORD dst_unused:UNUSED_PAD src0_sel:WORD_1 src1_sel:DWORD
	v_and_b32_sdwa v5, v0, v181 dst_sel:DWORD dst_unused:UNUSED_PAD src0_sel:WORD_1 src1_sel:DWORD
	v_add3_u32 v0, v0, v5, s98
	v_add3_u32 v1, v1, v4, s98
	v_and_b32_sdwa v4, v3, v181 dst_sel:DWORD dst_unused:UNUSED_PAD src0_sel:WORD_1 src1_sel:DWORD
	v_and_b32_sdwa v5, v2, v181 dst_sel:DWORD dst_unused:UNUSED_PAD src0_sel:WORD_1 src1_sel:DWORD
	v_add3_u32 v3, v3, v4, s98
	v_add3_u32 v2, v2, v5, s98
	v_and_b32_e32 v3, 0xffff0000, v3
	v_and_b32_e32 v2, 0xffff0000, v2
	s_mov_b64 s[48:49], 0x1c000
	v_or_b32_sdwa v1, v3, v1 dst_sel:DWORD dst_unused:UNUSED_PAD src0_sel:DWORD src1_sel:WORD_1
	v_or_b32_sdwa v0, v2, v0 dst_sel:DWORD dst_unused:UNUSED_PAD src0_sel:DWORD src1_sel:WORD_1
	s_add_i32 s3, s3, 64
	v_lshl_add_u64 v[158:159], v[158:159], 0, s[48:49]
	s_mov_b64 s[48:49], 0x10000
	s_add_i32 s46, s46, 1
	v_add_u32_e32 v149, 0x1200, v149
	global_store_dwordx2 v[160:161], v[0:1], off offset:48
	v_lshl_add_u64 v[160:161], v[160:161], 0, s[48:49]
	s_cmpk_eq_i32 s3, 0x100
	v_add_u32_e32 v143, 0x400, v143
	s_cbranch_scc1 .LBB0_446

; #define LAS __attribute__((address_space(3)))
; __device__ __forceinline__ unsigned pk2(float lo, float hi) { return f2bf(lo) | (f2bf(hi) << 16); }
; __device__ __forceinline__ void attn_conv_unit(LAS unsigned char* lds, int unit, const bf16* Z, bf16* Y, float* RA,
;                                                const float* qg, const float* kg, const float* sinks, const float* convw) {
;     ...
;             const float NEG = -1e30f;
; #pragma unroll
;             for (int r = 0; r < 16; ++r) { const int c = (r & 3) + 8 * (r >> 2) + 4 * hi;
;                 if (!(r32 < c)) s[0][r] = NEG;
;                 if (!(r32 >= c)) s[4][r] = NEG; }
;             if (qb == 0) {
; #pragma unroll
;                 for (int a = 0; a < 5; ++a) if (j + a < 4) {
; #pragma unroll
;                     for (int r = 0; r < 16; ++r) s[a][r] = NEG; }
;             }
;             float mx = sink2;
; #pragma unroll
;             for (int a = 0; a < 5; ++a)
; #pragma unroll
;                 for (int r = 0; r < 16; ++r) mx = fmaxf(mx, s[a][r]);
;             mx = fmaxf(mx, __shfl_xor(mx, 32));
;             float l = 0.f;
; #pragma unroll
;             for (int a = 0; a < 5; ++a)
; #pragma unroll
;                 for (int r = 0; r < 16; ++r) { const float p = __builtin_amdgcn_exp2f(s[a][r] - mx); s[a][r] = p; l += p; }
;             l += __shfl_xor(l, 32);
;             l += __builtin_amdgcn_exp2f(sink2 - mx);
;             f32x16 o[2]; o[0] = (f32x16){}; o[1] = (f32x16){};
; #pragma unroll
;             for (int a = 0; a < 5; ++a)
; #pragma unroll
;                 for (int h2 = 0; h2 < 2; ++h2) {
;                     v4u pw; pw.x = pk2(s[a][8 * h2 + 0], s[a][8 * h2 + 1]); pw.y = pk2(s[a][8 * h2 + 2], s[a][8 * h2 + 3]); pw.z = pk2(s[a][8 * h2 + 4], s[a][8 * h2 + 5]); pw.w = pk2(s[a][8 * h2 + 6], s[a][8 * h2 + 7]);
;                     const bf16x8 pf = __builtin_bit_cast(bf16x8, pw);
; #pragma unroll
;                     for (int dt = 0; dt < 2; ++dt) {
;                         const LAS unsigned char* vp = vtb + dt * 32 * VT_STRIDE + (32 * (j + a) + 16 * h2) * 2;
;                         const v2u lo = *(const LAS v2u*)(vp), hi2 = *(const LAS v2u*)(vp + 16);
;                         const v4u vw = (v4u){lo.x, lo.y, hi2.x, hi2.y};
;                         o[dt] = __builtin_amdgcn_mfma_f32_32x32x16_bf16(__builtin_bit_cast(bf16x8, vw), pf, o[dt], 0, 0, 0);
.LBB0_444:
	v_cndmask_b32_e64 v187, v180, v49, s[12:13]
	v_max3_f32 v49, v147, v64, v65
	v_max3_f32 v49, v49, v66, v67
	v_max3_f32 v49, v49, v68, v69
	v_max3_f32 v49, v49, v70, v71
	v_max3_f32 v49, v49, v72, v73
	v_max3_f32 v49, v49, v74, v75
	v_max3_f32 v49, v49, v76, v77
	v_max3_f32 v49, v49, v78, v79
	v_max3_f32 v49, v49, v32, v33
	v_max3_f32 v49, v49, v34, v35
	v_max3_f32 v49, v49, v36, v37
	v_max3_f32 v49, v49, v38, v39
	v_max3_f32 v49, v49, v40, v41
	v_max3_f32 v49, v49, v42, v43
	v_max3_f32 v49, v49, v44, v45
	v_max3_f32 v49, v49, v46, v47
	v_max3_f32 v49, v49, v16, v17
	v_max3_f32 v49, v49, v18, v19
	v_max3_f32 v49, v49, v20, v21
	v_max3_f32 v49, v49, v22, v23
	v_max3_f32 v49, v49, v24, v25
	v_max3_f32 v49, v49, v26, v27
	v_max3_f32 v49, v49, v28, v29
	v_max3_f32 v49, v49, v30, v31
	v_max3_f32 v49, v49, v0, v1
	v_max3_f32 v49, v49, v2, v3
	v_max3_f32 v49, v49, v4, v5
	v_max3_f32 v49, v49, v6, v7
	v_max3_f32 v49, v49, v8, v9
	v_max3_f32 v49, v49, v10, v11
	v_cndmask_b32_e64 v96, v48, v180, s[10:11]
	v_max3_f32 v49, v49, v12, v13
	v_cndmask_b32_e64 v48, v96, v48, s[12:13]
	v_max3_f32 v49, v49, v14, v15
	v_cndmask_b32_e64 v188, v50, v180, s[14:15]
	v_cndmask_b32_e64 v189, v51, v180, s[16:17]
	v_max3_f32 v49, v49, v48, v187
	v_cndmask_b32_e64 v190, v52, v180, s[18:19]
	v_cndmask_b32_e64 v191, v53, v180, s[20:21]
	v_max3_f32 v49, v49, v188, v189
	v_cndmask_b32_e64 v192, v54, v180, s[22:23]
	v_cndmask_b32_e64 v193, v55, v180, s[24:25]
	v_max3_f32 v49, v49, v190, v191
	v_cndmask_b32_e64 v194, v56, v180, s[26:27]
	v_cndmask_b32_e64 v195, v57, v180, s[28:29]
	v_max3_f32 v49, v49, v192, v193
	v_cndmask_b32_e64 v196, v58, v180, s[30:31]
	v_cndmask_b32_e64 v197, v59, v180, s[34:35]
	v_max3_f32 v49, v49, v194, v195
	v_cndmask_b32_e64 v198, v60, v180, s[36:37]
	v_cndmask_b32_e64 v199, v61, v180, s[38:39]
	v_max3_f32 v49, v49, v196, v197
	v_cndmask_b32_e64 v200, v62, v180, s[40:41]
	v_cndmask_b32_e64 v201, v63, v180, s[42:43]
	v_max3_f32 v49, v49, v198, v199
	v_max3_f32 v49, v49, v200, v201
	ds_bpermute_b32 v50, v165, v49
	s_waitcnt lgkmcnt(0)
	v_max_f32_e32 v50, v50, v50
	v_max_f32_e32 v202, v49, v50
	v_sub_f32_e32 v49, v64, v202
	v_sub_f32_e32 v0, v0, v202
	v_exp_f32_e32 v203, v49
	v_sub_f32_e32 v49, v65, v202
	v_exp_f32_e32 v65, v0
	v_sub_f32_e32 v0, v1, v202
	v_exp_f32_e32 v58, v0
	v_sub_f32_e32 v0, v2, v202
	v_exp_f32_e32 v204, v49
	v_sub_f32_e32 v49, v66, v202
	v_exp_f32_e32 v59, v0
	v_sub_f32_e32 v0, v3, v202
	v_exp_f32_e32 v205, v49
	v_sub_f32_e32 v49, v67, v202
	v_exp_f32_e32 v60, v0
	v_sub_f32_e32 v0, v4, v202
	v_exp_f32_e32 v206, v49
	v_sub_f32_e32 v49, v68, v202
	v_exp_f32_e32 v61, v0
	v_sub_f32_e32 v0, v5, v202
	v_exp_f32_e32 v207, v49
	v_sub_f32_e32 v49, v69, v202
	v_exp_f32_e32 v62, v0
	v_sub_f32_e32 v0, v6, v202
	v_exp_f32_e32 v208, v49
	v_sub_f32_e32 v49, v70, v202
	v_exp_f32_e32 v63, v0
	v_sub_f32_e32 v0, v7, v202
	v_exp_f32_e32 v209, v49
	v_sub_f32_e32 v49, v71, v202
	v_sub_f32_e32 v32, v32, v202
	v_exp_f32_e32 v64, v0
	v_sub_f32_e32 v0, v8, v202
	v_exp_f32_e32 v210, v49
	v_sub_f32_e32 v49, v72, v202
	v_exp_f32_e32 v219, v32
	v_sub_f32_e32 v32, v33, v202
	v_exp_f32_e32 v57, v0
	v_sub_f32_e32 v0, v9, v202
	v_exp_f32_e32 v211, v49
	v_sub_f32_e32 v49, v73, v202
	v_exp_f32_e32 v155, v32
	v_sub_f32_e32 v32, v34, v202
	v_exp_f32_e32 v50, v0
	v_sub_f32_e32 v0, v10, v202
	v_exp_f32_e32 v212, v49
	v_sub_f32_e32 v49, v74, v202
	v_exp_f32_e32 v157, v32
	v_sub_f32_e32 v32, v35, v202
	v_exp_f32_e32 v51, v0
	v_sub_f32_e32 v0, v11, v202
	v_exp_f32_e32 v213, v49
	v_sub_f32_e32 v49, v75, v202
	v_exp_f32_e32 v182, v32
	v_sub_f32_e32 v32, v36, v202
	v_exp_f32_e32 v52, v0
	v_sub_f32_e32 v0, v12, v202
	v_exp_f32_e32 v214, v49
	v_sub_f32_e32 v49, v76, v202
	v_exp_f32_e32 v183, v32
	v_sub_f32_e32 v32, v37, v202
	v_exp_f32_e32 v53, v0
	v_sub_f32_e32 v0, v13, v202
	v_exp_f32_e32 v215, v49
	v_sub_f32_e32 v49, v77, v202
	v_exp_f32_e32 v184, v32
	v_sub_f32_e32 v32, v38, v202
	v_exp_f32_e32 v54, v0
	v_sub_f32_e32 v0, v14, v202
	v_exp_f32_e32 v216, v49
	v_sub_f32_e32 v49, v78, v202
	v_exp_f32_e32 v185, v32
	v_sub_f32_e32 v32, v39, v202
	v_exp_f32_e32 v55, v0
	v_sub_f32_e32 v0, v15, v202
	v_exp_f32_e32 v217, v49
	v_sub_f32_e32 v49, v79, v202
	v_exp_f32_e32 v186, v32
	v_sub_f32_e32 v32, v40, v202
	v_exp_f32_e32 v56, v0
	v_sub_f32_e32 v0, v48, v202
	v_exp_f32_e32 v218, v49
	v_exp_f32_e32 v153, v32
	v_sub_f32_e32 v32, v41, v202
	v_exp_f32_e32 v49, v0
	v_sub_f32_e32 v0, v187, v202
	v_exp_f32_e32 v98, v32
	v_sub_f32_e32 v32, v42, v202
	v_exp_f32_e32 v42, v0
	v_sub_f32_e32 v0, v188, v202
	v_exp_f32_e32 v99, v32
	v_sub_f32_e32 v32, v43, v202
	v_exp_f32_e32 v43, v0
	v_sub_f32_e32 v0, v189, v202
	v_exp_f32_e32 v100, v32
	v_sub_f32_e32 v32, v44, v202
	v_exp_f32_e32 v44, v0
	v_sub_f32_e32 v0, v190, v202
	v_exp_f32_e32 v101, v32
	v_sub_f32_e32 v32, v45, v202
	v_exp_f32_e32 v45, v0
	v_sub_f32_e32 v0, v191, v202
	v_exp_f32_e32 v102, v32
	v_sub_f32_e32 v32, v46, v202
	v_exp_f32_e32 v46, v0
	v_sub_f32_e32 v0, v192, v202
	v_exp_f32_e32 v103, v32
	v_sub_f32_e32 v32, v47, v202
	v_sub_f32_e32 v16, v16, v202
	v_exp_f32_e32 v47, v0
	v_sub_f32_e32 v0, v193, v202
	v_exp_f32_e32 v97, v16
	v_sub_f32_e32 v16, v17, v202
	v_exp_f32_e32 v48, v0
	v_sub_f32_e32 v0, v194, v202
	v_exp_f32_e32 v74, v16
	v_sub_f32_e32 v16, v18, v202
	v_exp_f32_e32 v34, v0
	v_sub_f32_e32 v0, v195, v202
	v_exp_f32_e32 v75, v16
	v_sub_f32_e32 v16, v19, v202
	v_exp_f32_e32 v37, v0
	v_sub_f32_e32 v0, v196, v202
	v_exp_f32_e32 v76, v16
	v_sub_f32_e32 v16, v20, v202
	v_exp_f32_e32 v35, v0
	v_sub_f32_e32 v0, v197, v202
	v_exp_f32_e32 v77, v16
	v_sub_f32_e32 v16, v21, v202
	v_exp_f32_e32 v39, v0
	v_sub_f32_e32 v0, v198, v202
	v_exp_f32_e32 v78, v16
	v_sub_f32_e32 v16, v22, v202
	v_exp_f32_e32 v36, v0
	v_sub_f32_e32 v0, v199, v202
	v_exp_f32_e32 v79, v16
	v_sub_f32_e32 v16, v23, v202
	v_exp_f32_e32 v40, v0
	v_sub_f32_e32 v0, v200, v202
	v_exp_f32_e32 v96, v16
	v_sub_f32_e32 v16, v24, v202
	v_exp_f32_e32 v38, v0
	v_sub_f32_e32 v0, v201, v202
	v_exp_f32_e32 v73, v16
	v_sub_f32_e32 v16, v25, v202
	v_exp_f32_e32 v41, v0
	v_sub_f32_e32 v0, v147, v202
	v_add_u32_e32 v33, s3, v145
	v_exp_f32_e32 v151, v32
	v_exp_f32_e32 v66, v16
	v_sub_f32_e32 v16, v26, v202
	v_exp_f32_e32 v32, v0
	v_add_u32_e32 v0, 0x12000, v33
	v_add_u32_e32 v2, 0x12010, v33
	v_exp_f32_e32 v67, v16
	v_sub_f32_e32 v16, v27, v202
	ds_read_b64 v[0:1], v0
	ds_read_b64 v[2:3], v2
	v_exp_f32_e32 v68, v16
	v_sub_f32_e32 v16, v28, v202
	v_exp_f32_e32 v69, v16
	v_sub_f32_e32 v16, v29, v202
	v_exp_f32_e32 v70, v16
	v_sub_f32_e32 v16, v30, v202
	v_exp_f32_e32 v71, v16
	v_sub_f32_e32 v16, v31, v202
	v_add_f32_e32 v12, 0, v203
	v_cvt_pk_bf16_f32 v7, v209, v210
	v_cvt_pk_bf16_f32 v6, v207, v208
	v_cvt_pk_bf16_f32 v5, v205, v206
	v_cvt_pk_bf16_f32 v4, v203, v204
	v_exp_f32_e32 v72, v16
	v_add_u32_e32 v8, 0x16100, v33
	s_waitcnt lgkmcnt(0)
; #define LAS __attribute__((address_space(3)))
; __device__ __forceinline__ unsigned pk2(float lo, float hi) { return f2bf(lo) | (f2bf(hi) << 16); }
; __device__ __forceinline__ void attn_conv_unit(LAS unsigned char* lds, int unit, const bf16* Z, bf16* Y, float* RA,
;                                                const float* qg, const float* kg, const float* sinks, const float* convw) {
;     ...
;             for (int a = 0; a < 5; ++a)
; #pragma unroll
;                 for (int r = 0; r < 16; ++r) { const float p = __builtin_amdgcn_exp2f(s[a][r] - mx); s[a][r] = p; l += p; }
;             l += __shfl_xor(l, 32);
;             l += __builtin_amdgcn_exp2f(sink2 - mx);
;             f32x16 o[2]; o[0] = (f32x16){}; o[1] = (f32x16){};
; #pragma unroll
;             for (int a = 0; a < 5; ++a)
; #pragma unroll
;                 for (int h2 = 0; h2 < 2; ++h2) {
;                     v4u pw; pw.x = pk2(s[a][8 * h2 + 0], s[a][8 * h2 + 1]); pw.y = pk2(s[a][8 * h2 + 2], s[a][8 * h2 + 3]); pw.z = pk2(s[a][8 * h2 + 4], s[a][8 * h2 + 5]); pw.w = pk2(s[a][8 * h2 + 6], s[a][8 * h2 + 7]);
;                     const bf16x8 pf = __builtin_bit_cast(bf16x8, pw);
; #pragma unroll
;                     for (int dt = 0; dt < 2; ++dt) {
;                         const LAS unsigned char* vp = vtb + dt * 32 * VT_STRIDE + (32 * (j + a) + 16 * h2) * 2;
;                         const v2u lo = *(const LAS v2u*)(vp), hi2 = *(const LAS v2u*)(vp + 16);
;                         const v4u vw = (v4u){lo.x, lo.y, hi2.x, hi2.y};
;                         o[dt] = __builtin_amdgcn_mfma_f32_32x32x16_bf16(__builtin_bit_cast(bf16x8, vw), pf, o[dt], 0, 0, 0);
	v_mfma_f32_32x32x16_bf16 v[16:31], v[0:3], v[4:7], 0
	v_add_f32_e32 v0, v204, v12
	v_add_u32_e32 v10, 0x16110, v33
	v_add_f32_e32 v0, v205, v0
	ds_read_b64 v[8:9], v8
	ds_read_b64 v[10:11], v10
	v_add_f32_e32 v0, v206, v0
	v_add_f32_e32 v0, v207, v0
	v_add_f32_e32 v0, v208, v0
	v_add_f32_e32 v0, v209, v0
	v_add_f32_e32 v187, v210, v0
	s_waitcnt lgkmcnt(0)
	v_mfma_f32_32x32x16_bf16 v[0:15], v[8:11], v[4:7], 0
	v_add_f32_e32 v187, v211, v187
	v_add_f32_e32 v187, v212, v187
	v_add_u32_e32 v188, 0x12020, v33
	v_add_u32_e32 v190, 0x12030, v33
	v_cvt_pk_bf16_f32 v194, v215, v216
	v_cvt_pk_bf16_f32 v192, v211, v212
	v_add_u32_e32 v196, 0x16120, v33
	v_add_u32_e32 v198, 0x16130, v33
	v_add_f32_e32 v187, v213, v187
	ds_read_b64 v[188:189], v188
	ds_read_b64 v[190:191], v190
	v_cvt_pk_bf16_f32 v195, v217, v218
	v_cvt_pk_bf16_f32 v193, v213, v214
	ds_read_b64 v[196:197], v196
	ds_read_b64 v[198:199], v198
	v_add_f32_e32 v187, v214, v187
	v_add_f32_e32 v187, v215, v187
	v_add_f32_e32 v187, v216, v187
	v_add_f32_e32 v187, v217, v187
	v_add_f32_e32 v187, v218, v187
	s_waitcnt lgkmcnt(2)
	v_mfma_f32_32x32x16_bf16 v[16:31], v[188:191], v[192:195], v[16:31]
	v_add_f32_e32 v187, v219, v187
	v_add_u32_e32 v188, 0x12040, v33
	s_waitcnt lgkmcnt(0)
	v_mfma_f32_32x32x16_bf16 v[0:15], v[196:199], v[192:195], v[0:15]
	v_bfe_u32 v192, v155, 16, 1
	v_add3_u32 v192, v155, v192, s98
	v_add_f32_e32 v155, v155, v187
	v_bfe_u32 v189, v219, 16, 1
	v_add_f32_e32 v155, v157, v155
	v_add3_u32 v189, v219, v189, s98
	v_add_u32_e32 v190, 0x12050, v33
	v_add_f32_e32 v155, v182, v155
	v_lshrrev_b32_e32 v197, 16, v189
	ds_read_b64 v[188:189], v188
	ds_read_b64 v[190:191], v190
	v_cvt_pk_bf16_f32 v195, v185, v186
	v_cvt_pk_bf16_f32 v193, v157, v182
	v_add_u32_e32 v196, 0x16140, v33
	v_add_u32_e32 v198, 0x16150, v33
	v_add_f32_e32 v155, v183, v155
	v_cvt_pk_bf16_f32 v194, v183, v184
	v_and_or_b32 v192, v192, s96, v197
	ds_read_b64 v[196:197], v196
	ds_read_b64 v[198:199], v198
	v_add_f32_e32 v155, v184, v155
	v_add_f32_e32 v155, v185, v155
	v_add_f32_e32 v155, v186, v155
	v_add_f32_e32 v155, v153, v155
	v_bfe_u32 v184, v98, 16, 1
	s_waitcnt lgkmcnt(2)
	v_mfma_f32_32x32x16_bf16 v[16:31], v[188:191], v[192:195], v[16:31]
	v_add3_u32 v186, v98, v184, s98
	v_bfe_u32 v182, v153, 16, 1
	v_add_f32_e32 v98, v98, v155
	s_waitcnt lgkmcnt(0)
	v_mfma_f32_32x32x16_bf16 v[0:15], v[196:199], v[192:195], v[0:15]
	v_add3_u32 v153, v153, v182, s98
	v_add_f32_e32 v98, v99, v98
	v_lshrrev_b32_e32 v153, 16, v153
	v_add_u32_e32 v182, 0x12060, v33
	v_add_u32_e32 v184, 0x12070, v33
	v_add_f32_e32 v98, v100, v98
	ds_read_b64 v[182:183], v182
	ds_read_b64 v[184:185], v184
	v_and_or_b32 v186, v186, s96, v153
	v_add_u32_e32 v153, 0x16160, v33
	v_add_f32_e32 v98, v101, v98
	v_cvt_pk_bf16_f32 v189, v103, v151
	v_cvt_pk_bf16_f32 v188, v101, v102
	v_cvt_pk_bf16_f32 v187, v99, v100
	v_add_u32_e32 v157, 0x16170, v33
	ds_read_b64 v[190:191], v153
	ds_read_b64 v[192:193], v157
	v_add_f32_e32 v98, v102, v98
	v_add_f32_e32 v98, v103, v98
	v_add_f32_e32 v98, v151, v98
	v_add_f32_e32 v102, v97, v98
	v_bfe_u32 v103, v74, 16, 1
	s_waitcnt lgkmcnt(2)
	v_mfma_f32_32x32x16_bf16 v[16:31], v[182:185], v[186:189], v[16:31]
	v_add3_u32 v103, v74, v103, s98
	v_bfe_u32 v98, v97, 16, 1
	v_add_f32_e32 v74, v74, v102
	s_waitcnt lgkmcnt(0)
	v_mfma_f32_32x32x16_bf16 v[0:15], v[190:193], v[186:189], v[0:15]
	v_add3_u32 v97, v97, v98, s98
	v_add_f32_e32 v74, v75, v74
	v_add_u32_e32 v99, 0x12080, v33
	v_lshrrev_b32_e32 v97, 16, v97
	v_add_u32_e32 v100, 0x12090, v33
	v_add_f32_e32 v74, v76, v74
	ds_read_b64 v[98:99], v99
	ds_read_b64 v[100:101], v100
	v_cvt_pk_bf16_f32 v184, v77, v78
	v_cvt_pk_bf16_f32 v183, v75, v76
	v_and_or_b32 v182, v103, s96, v97
	v_add_u32_e32 v97, 0x16180, v33
	v_add_f32_e32 v74, v77, v74
	v_add_u32_e32 v103, 0x16190, v33
	ds_read_b64 v[186:187], v97
	ds_read_b64 v[188:189], v103
	v_add_f32_e32 v74, v78, v74
	v_add_f32_e32 v74, v79, v74
	v_add_f32_e32 v74, v96, v74
	v_cvt_pk_bf16_f32 v185, v79, v96
	v_add_f32_e32 v78, v73, v74
	v_bfe_u32 v77, v66, 16, 1
	s_waitcnt lgkmcnt(2)
	v_mfma_f32_32x32x16_bf16 v[16:31], v[98:101], v[182:185], v[16:31]
	v_add3_u32 v79, v66, v77, s98
	v_bfe_u32 v74, v73, 16, 1
	v_add_f32_e32 v66, v66, v78
	s_waitcnt lgkmcnt(0)
	v_mfma_f32_32x32x16_bf16 v[0:15], v[186:189], v[182:185], v[0:15]
	v_add3_u32 v73, v73, v74, s98
	v_add_f32_e32 v66, v67, v66
	v_lshrrev_b32_e32 v73, 16, v73
	v_add_f32_e32 v66, v68, v66
	v_add_u32_e32 v74, 0x120a0, v33
	v_add_u32_e32 v76, 0x120b0, v33
	v_cvt_pk_bf16_f32 v99, v71, v72
	v_cvt_pk_bf16_f32 v98, v69, v70
	v_cvt_pk_bf16_f32 v97, v67, v68
	v_and_or_b32 v96, v79, s96, v73
	v_add_u32_e32 v73, 0x161a0, v33
	v_add_f32_e32 v66, v69, v66
	ds_read_b64 v[74:75], v74
	ds_read_b64 v[76:77], v76
	v_add_u32_e32 v79, 0x161b0, v33
	ds_read_b64 v[100:101], v73
	ds_read_b64 v[102:103], v79
	v_add_f32_e32 v66, v70, v66
	v_add_f32_e32 v66, v71, v66
	v_add_f32_e32 v66, v72, v66
	v_add_f32_e32 v78, v65, v66
	v_bfe_u32 v66, v65, 16, 1
	s_waitcnt lgkmcnt(2)
	v_mfma_f32_32x32x16_bf16 v[16:31], v[74:77], v[96:99], v[16:31]
	v_bfe_u32 v70, v58, 16, 1
	v_add3_u32 v65, v65, v66, s98
	v_add3_u32 v70, v58, v70, s98
	s_waitcnt lgkmcnt(0)
	v_mfma_f32_32x32x16_bf16 v[0:15], v[100:103], v[96:99], v[0:15]
	v_lshrrev_b32_e32 v65, 16, v65
	v_add_f32_e32 v58, v58, v78
	v_add_u32_e32 v67, 0x120c0, v33
	v_add_u32_e32 v68, 0x120d0, v33
	v_cvt_pk_bf16_f32 v72, v61, v62
	v_and_or_b32 v70, v70, s96, v65
	v_add_u32_e32 v65, 0x161c0, v33
	v_add_u32_e32 v76, 0x161d0, v33
	v_add_f32_e32 v58, v59, v58
	ds_read_b64 v[66:67], v67
	ds_read_b64 v[68:69], v68
	v_cvt_pk_bf16_f32 v73, v63, v64
	v_cvt_pk_bf16_f32 v71, v59, v60
	ds_read_b64 v[74:75], v65
	ds_read_b64 v[76:77], v76
	v_add_f32_e32 v58, v60, v58
	v_add_f32_e32 v58, v61, v58
	v_add_f32_e32 v58, v62, v58
	v_add_f32_e32 v58, v63, v58
	v_add_f32_e32 v58, v64, v58
	s_waitcnt lgkmcnt(2)
; #define LAS __attribute__((address_space(3)))
; __device__ __forceinline__ unsigned pk2(float lo, float hi) { return f2bf(lo) | (f2bf(hi) << 16); }
; __device__ __forceinline__ void attn_conv_unit(LAS unsigned char* lds, int unit, const bf16* Z, bf16* Y, float* RA,
;                                                const float* qg, const float* kg, const float* sinks, const float* convw) {
;     ...
; #pragma unroll
;             for (int a = 0; a < 5; ++a)
; #pragma unroll
;                 for (int h2 = 0; h2 < 2; ++h2) {
;                     v4u pw; pw.x = pk2(s[a][8 * h2 + 0], s[a][8 * h2 + 1]); pw.y = pk2(s[a][8 * h2 + 2], s[a][8 * h2 + 3]); pw.z = pk2(s[a][8 * h2 + 4], s[a][8 * h2 + 5]); pw.w = pk2(s[a][8 * h2 + 6], s[a][8 * h2 + 7]);
;                     const bf16x8 pf = __builtin_bit_cast(bf16x8, pw);
; #pragma unroll
;                     for (int dt = 0; dt < 2; ++dt) {
;                         const LAS unsigned char* vp = vtb + dt * 32 * VT_STRIDE + (32 * (j + a) + 16 * h2) * 2;
;                         const v2u lo = *(const LAS v2u*)(vp), hi2 = *(const LAS v2u*)(vp + 16);
;                         const v4u vw = (v4u){lo.x, lo.y, hi2.x, hi2.y};
;                         o[dt] = __builtin_amdgcn_mfma_f32_32x32x16_bf16(__builtin_bit_cast(bf16x8, vw), pf, o[dt], 0, 0, 0);
;                     }
;                 }
;             const float inv = 1.0f / l;
;             float sq = 0.f;
; #pragma unroll
;             for (int dt = 0; dt < 2; ++dt)
; #pragma unroll
;                 for (int r = 0; r < 16; ++r) { o[dt][r] *= inv; sq += o[dt][r] * o[dt][r]; }
;             sq += __shfl_xor(sq, 32);
;             if (hi == 0) SS[(32 * j + r32) * 8 + h] = sq;
	v_mfma_f32_32x32x16_bf16 v[16:31], v[66:69], v[70:73], v[16:31]
	v_bfe_u32 v61, v50, 16, 1
	v_add3_u32 v62, v50, v61, s98
	s_waitcnt lgkmcnt(0)
	v_mfma_f32_32x32x16_bf16 v[0:15], v[74:77], v[70:73], v[0:15]
	v_add_f32_e32 v70, v57, v58
	v_bfe_u32 v58, v57, 16, 1
	v_add3_u32 v57, v57, v58, s98
	v_lshrrev_b32_e32 v57, 16, v57
	v_add_f32_e32 v50, v50, v70
	v_add_u32_e32 v58, 0x120e0, v33
	v_add_u32_e32 v60, 0x120f0, v33
	v_cvt_pk_bf16_f32 v65, v55, v56
	v_and_or_b32 v62, v62, s96, v57
	v_add_u32_e32 v57, 0x161e0, v33
	v_add_u32_e32 v68, 0x161f0, v33
	v_add_f32_e32 v50, v51, v50
	ds_read_b64 v[58:59], v58
	ds_read_b64 v[60:61], v60
	v_cvt_pk_bf16_f32 v64, v53, v54
	v_cvt_pk_bf16_f32 v63, v51, v52
	ds_read_b64 v[66:67], v57
	ds_read_b64 v[68:69], v68
	v_add_f32_e32 v50, v52, v50
	v_add_f32_e32 v50, v53, v50
	v_add_f32_e32 v50, v54, v50
	v_add_f32_e32 v50, v55, v50
	v_add_f32_e32 v50, v56, v50
	s_waitcnt lgkmcnt(2)
	v_mfma_f32_32x32x16_bf16 v[16:31], v[58:61], v[62:65], v[16:31]
	v_bfe_u32 v54, v42, 16, 1
	v_add3_u32 v54, v42, v54, s98
	s_waitcnt lgkmcnt(0)
	v_mfma_f32_32x32x16_bf16 v[0:15], v[66:69], v[62:65], v[0:15]
	v_add_f32_e32 v62, v49, v50
	v_add_f32_e32 v42, v42, v62
	v_add_f32_e32 v42, v43, v42
	v_add_f32_e32 v42, v44, v42
	v_add_f32_e32 v42, v45, v42
	v_add_f32_e32 v42, v46, v42
	v_add_f32_e32 v42, v47, v42
	v_add_f32_e32 v42, v48, v42
	v_add_f32_e32 v42, v34, v42
	v_add_f32_e32 v42, v37, v42
	v_add_u32_e32 v51, 0x12100, v33
	v_bfe_u32 v50, v49, 16, 1
	v_add_u32_e32 v52, 0x12110, v33
	v_add_f32_e32 v42, v35, v42
	v_add3_u32 v49, v49, v50, s98
	ds_read_b64 v[50:51], v51
	ds_read_b64 v[52:53], v52
	v_add_f32_e32 v42, v39, v42
	v_add_f32_e32 v42, v36, v42
	v_add_f32_e32 v42, v40, v42
	v_lshrrev_b32_e32 v49, 16, v49
	v_add_f32_e32 v42, v38, v42
	v_cvt_pk_bf16_f32 v57, v47, v48
	v_cvt_pk_bf16_f32 v56, v45, v46
	v_cvt_pk_bf16_f32 v55, v43, v44
	v_and_or_b32 v54, v54, s96, v49
	v_add_f32_e32 v46, v41, v42
	v_bfe_u32 v43, v40, 16, 1
	v_bfe_u32 v45, v37, 16, 1
	v_add_u32_e32 v49, 0x16200, v33
	v_add_u32_e32 v60, 0x16210, v33
	s_waitcnt lgkmcnt(0)
	v_mfma_f32_32x32x16_bf16 v[16:31], v[50:53], v[54:57], v[16:31]
	ds_bpermute_b32 v47, v165, v46
	v_bfe_u32 v42, v41, 16, 1
	v_bfe_u32 v44, v39, 16, 1
	v_add3_u32 v45, v37, v45, s98
	v_add3_u32 v40, v40, v43, s98
	v_bfe_u32 v37, v34, 16, 1
	v_bfe_u32 v43, v36, 16, 1
	ds_read_b64 v[58:59], v49
	ds_read_b64 v[60:61], v60
	v_add3_u32 v39, v39, v44, s98
	v_add3_u32 v41, v41, v42, s98
	v_bfe_u32 v42, v35, 16, 1
	v_bfe_u32 v44, v38, 16, 1
	v_add3_u32 v36, v36, v43, s98
	v_add3_u32 v34, v34, v37, s98
	v_add3_u32 v38, v38, v44, s98
	v_add3_u32 v35, v35, v42, s98
	v_lshrrev_b32_e32 v42, 16, v34
	v_lshrrev_b32_e32 v44, 16, v36
	v_add_u32_e32 v34, 0x12120, v33
	v_add_u32_e32 v36, 0x12130, v33
	v_lshrrev_b32_e32 v43, 16, v35
	v_lshrrev_b32_e32 v38, 16, v38
	ds_read_b64 v[34:35], v34
	ds_read_b64 v[36:37], v36
	v_and_or_b32 v41, v41, s96, v38
	v_and_or_b32 v38, v45, s96, v42
	v_add_u32_e32 v42, 0x16220, v33
	v_add_u32_e32 v33, 0x16230, v33
	v_and_or_b32 v40, v40, s96, v44
	v_and_or_b32 v39, v39, s96, v43
	ds_read_b64 v[42:43], v42
	ds_read_b64 v[44:45], v33
	s_waitcnt lgkmcnt(6)
	v_add_f32_e32 v33, v46, v47
	s_waitcnt lgkmcnt(4)
	v_mfma_f32_32x32x16_bf16 v[0:15], v[58:61], v[54:57], v[0:15]
	v_add_f32_e32 v32, v32, v33
	v_div_scale_f32 v33, s[48:49], v32, v32, 1.0
	s_waitcnt lgkmcnt(2)
	v_mfma_f32_32x32x16_bf16 v[16:31], v[34:37], v[38:41], v[16:31]
	v_rcp_f32_e32 v34, v33
	s_nop 0
	v_fma_f32 v35, -v33, v34, 1.0
	v_fmac_f32_e32 v34, v35, v34
	v_div_scale_f32 v35, vcc, 1.0, v32, 1.0
	s_waitcnt lgkmcnt(0)
	v_mfma_f32_32x32x16_bf16 v[0:15], v[42:45], v[38:41], v[0:15]
	v_mul_f32_e32 v36, v35, v34
	v_fma_f32 v37, -v33, v36, v35
	v_fmac_f32_e32 v36, v37, v34
	v_fma_f32 v33, -v33, v36, v35
	v_div_fmas_f32 v33, v33, v34, v36
	v_div_fixup_f32 v44, v33, v32, 1.0
	v_mov_b32_e32 v32, v16
	v_mov_b32_e32 v33, v18
	v_mov_b32_e32 v18, v17
	v_mov_b32_e32 v16, v20
	v_mov_b32_e32 v17, v22
	v_pk_mul_f32 v[36:37], v[16:17], v[44:45] op_sel_hi:[1,0]
	v_mov_b32_e32 v16, v24
	v_mov_b32_e32 v17, v26
	v_pk_mul_f32 v[40:41], v[32:33], v[44:45] op_sel_hi:[1,0]
	v_pk_mul_f32 v[32:33], v[16:17], v[44:45] op_sel_hi:[1,0]
	v_mov_b32_e32 v16, v28
	v_mov_b32_e32 v17, v30
	v_mov_b32_e32 v26, v25
	v_pk_mul_f32 v[24:25], v[16:17], v[44:45] op_sel_hi:[1,0]
	v_mov_b32_e32 v16, v0
	v_mov_b32_e32 v17, v2
	v_mov_b32_e32 v2, v1
	v_mov_b32_e32 v0, v4
	v_mov_b32_e32 v1, v6
	v_pk_mul_f32 v[42:43], v[18:19], v[44:45] op_sel_hi:[1,0]
	v_mov_b32_e32 v22, v21
	v_pk_mul_f32 v[20:21], v[16:17], v[44:45] op_sel_hi:[1,0]
	v_pk_mul_f32 v[16:17], v[0:1], v[44:45] op_sel_hi:[1,0]
	v_mov_b32_e32 v0, v8
	v_mov_b32_e32 v1, v10
	v_pk_mul_f32 v[46:47], v[40:41], v[40:41]
	v_pk_mul_f32 v[48:49], v[42:43], v[42:43]
	v_mov_b32_e32 v6, v5
	v_pk_mul_f32 v[4:5], v[0:1], v[44:45] op_sel_hi:[1,0]
	v_mov_b32_e32 v1, v14
	v_mov_b32_e32 v14, v13
	v_pk_mul_f32 v[38:39], v[22:23], v[44:45] op_sel_hi:[1,0]
	v_pk_mul_f32 v[22:23], v[2:3], v[44:45] op_sel_hi:[1,0]
	v_pk_mul_f32 v[2:3], v[14:15], v[44:45] op_sel_hi:[1,0]
	v_add_f32_e32 v14, v46, v48
	v_add_f32_e32 v14, v47, v14
	v_pk_mul_f32 v[50:51], v[36:37], v[36:37]
	v_add_f32_e32 v14, v49, v14
	v_pk_mul_f32 v[52:53], v[38:39], v[38:39]
	v_add_f32_e32 v14, v50, v14
	v_add_f32_e32 v14, v52, v14
	v_add_f32_e32 v14, v51, v14
	v_pk_mul_f32 v[54:55], v[32:33], v[32:33]
	v_pk_mul_f32 v[34:35], v[26:27], v[44:45] op_sel_hi:[1,0]
	v_add_f32_e32 v14, v53, v14
	v_pk_mul_f32 v[56:57], v[34:35], v[34:35]
	v_add_f32_e32 v14, v54, v14
	v_add_f32_e32 v14, v56, v14
	v_mov_b32_e32 v30, v29
	v_add_f32_e32 v14, v55, v14
	v_pk_mul_f32 v[58:59], v[24:25], v[24:25]
	v_pk_mul_f32 v[26:27], v[30:31], v[44:45] op_sel_hi:[1,0]
	v_add_f32_e32 v14, v57, v14
	v_pk_mul_f32 v[28:29], v[26:27], v[26:27]
	v_add_f32_e32 v14, v58, v14
	v_add_f32_e32 v14, v28, v14
	v_add_f32_e32 v14, v59, v14
	v_pk_mul_f32 v[30:31], v[20:21], v[20:21]
	v_add_f32_e32 v14, v29, v14
	v_pk_mul_f32 v[60:61], v[22:23], v[22:23]
	v_add_f32_e32 v14, v30, v14
	v_add_f32_e32 v14, v60, v14
	v_add_f32_e32 v14, v31, v14
	v_pk_mul_f32 v[62:63], v[16:17], v[16:17]
	v_pk_mul_f32 v[18:19], v[6:7], v[44:45] op_sel_hi:[1,0]
	v_add_f32_e32 v14, v61, v14
	v_pk_mul_f32 v[64:65], v[18:19], v[18:19]
	v_add_f32_e32 v14, v62, v14
	v_add_f32_e32 v14, v64, v14
	v_mov_b32_e32 v10, v9
	v_add_f32_e32 v14, v63, v14
	v_pk_mul_f32 v[66:67], v[4:5], v[4:5]
	v_pk_mul_f32 v[6:7], v[10:11], v[44:45] op_sel_hi:[1,0]
	v_add_f32_e32 v14, v65, v14
	v_pk_mul_f32 v[8:9], v[6:7], v[6:7]
	v_add_f32_e32 v14, v66, v14
	v_mov_b32_e32 v0, v12
	v_add_f32_e32 v8, v8, v14
	v_pk_mul_f32 v[0:1], v[0:1], v[44:45] op_sel_hi:[1,0]
	v_add_f32_e32 v8, v67, v8
	v_pk_mul_f32 v[10:11], v[0:1], v[0:1]
	v_add_f32_e32 v8, v9, v8
	v_pk_mul_f32 v[12:13], v[2:3], v[2:3]
	v_add_f32_e32 v8, v10, v8
	v_add_f32_e32 v8, v12, v8
	v_add_f32_e32 v8, v11, v8
	v_add_f32_e32 v8, v13, v8
	ds_bpermute_b32 v9, v165, v8
	s_and_saveexec_b64 s[48:49], s[8:9]
	s_cbranch_execz .LBB0_438
; __device__ __forceinline__ void attn_conv_unit(LAS unsigned char* lds, int unit, const bf16* Z, bf16* Y, float* RA,
;                                                const float* qg, const float* kg, const float* sinks, const float* convw) {
;     ...
;             sq += __shfl_xor(sq, 32);
;             if (hi == 0) SS[(32 * j + r32) * 8 + h] = sq;
	s_waitcnt lgkmcnt(0)
	v_add_f32_e32 v8, v8, v9
	ds_write_b32 v143, v8
	s_branch .LBB0_438

; __host__ __device__ __forceinline__ size_t blk_off(int row, int col, int K) { return ((size_t)(row >> 8) * (K >> 6) + (col >> 6)) * (256 * 64) + (size_t)(row & 255) * 64 + (col & 63); }
;     __device__ __forceinline__ void operator()(const f32x4 (&acc)[2][2][4][2], const Unit& u, int wr, int wc, int fr, int fq) const {
;     ...
;         for (int ai = 0; ai < 2; ++ai) {
;             u32x4 xw[4][2];
; #pragma unroll
;             for (int m = 0; m < 4; ++m)
; #pragma unroll
;                 for (int bj = 0; bj < 2; ++bj) xw[m][bj] = __builtin_nontemporal_load((const u32x4*)(x1b + blk_off(row0 + ai * HALF + m * 16, col0 + bj * HALF, 1024)));
;             asm volatile("" ::: "memory");
; #pragma unroll
;             for (int m = 0; m < 4; ++m) { const size_t off = (size_t)(row0 + ai * HALF + m * 16) * 1024 + col0;
; #pragma unroll
;                 for (int bj = 0; bj < 2; ++bj) {
;                     const u32x4 w = xw[m][bj];
;                     const f32x4 x0 = (f32x4){__builtin_bit_cast(float, w.x << 16), __builtin_bit_cast(float, w.x & 0xffff0000u), __builtin_bit_cast(float, w.y << 16), __builtin_bit_cast(float, w.y & 0xffff0000u)};
;                     const f32x4 x1 = (f32x4){__builtin_bit_cast(float, w.z << 16), __builtin_bit_cast(float, w.z & 0xffff0000u), __builtin_bit_cast(float, w.w << 16), __builtin_bit_cast(float, w.w & 0xffff0000u)};
;                     *(f32x4*)(out + off + bj * HALF) = x0 + acc[ai][bj][m][0]; *(f32x4*)(out + off + bj * HALF + 4) = x1 + acc[ai][bj][m][1]; } }
.LBB0_581:
	s_mov_b64 s[100:101], 0x4000
	s_lshl_b32 s0, s0, 8
	s_add_i32 s0, s0, s52
	s_lshl_b32 s21, s30, 8
	s_ashr_i32 s30, s0, 8
	s_ashr_i32 s31, s30, 31
	s_or_b32 s21, s21, s53
	s_lshl_b64 s[30:31], s[30:31], 19
	s_add_u32 s30, s10, s30
	v_or_b32_e32 v144, s0, v148
	v_bitop3_b32 v136, s21, 56, v149 bitop3:0xc8
	s_addc_u32 s31, s11, s31
	s_ashr_i32 s34, s21, 6
	v_lshlrev_b32_e32 v136, 1, v136
	s_ashr_i32 s35, s34, 31
	v_lshlrev_b32_e32 v145, 7, v144
	v_lshl_add_u64 v[142:143], s[30:31], 0, v[136:137]
	s_lshl_b64 s[30:31], s[34:35], 15
	v_and_b32_e32 v146, 0x6780, v145
	v_mov_b32_e32 v147, v137
	s_or_b32 s34, s34, 2
	v_lshl_add_u64 v[174:175], v[142:143], 0, v[146:147]
	s_ashr_i32 s35, s34, 31
	v_lshl_add_u64 v[142:143], v[174:175], 0, s[30:31]
	s_lshl_b64 s[34:35], s[34:35], 15
	v_lshl_add_u64 v[228:229], v[142:143], 0, s[100:101]
	global_load_dwordx4 v[196:199], v[228:229], off nt
	global_load_dwordx4 v[154:157], v[142:143], off nt
	v_lshl_add_u64 v[228:229], v[142:143], 0, s[100:101]
	global_load_dwordx4 v[204:207], v[228:229], off offset:2048 nt
	global_load_dwordx4 v[158:161], v[142:143], off offset:2048 nt
	v_lshl_add_u64 v[142:143], v[174:175], 0, s[34:35]
	v_lshl_add_u64 v[228:229], v[142:143], 0, s[100:101]
	global_load_dwordx4 v[200:203], v[228:229], off nt
	global_load_dwordx4 v[162:165], v[142:143], off nt
	v_lshl_add_u64 v[228:229], v[142:143], 0, s[100:101]
	global_load_dwordx4 v[208:211], v[228:229], off offset:2048 nt
	global_load_dwordx4 v[166:169], v[142:143], off offset:2048 nt
	v_lshl_add_u64 v[176:177], v[174:175], 0, s[8:9]
	v_lshl_add_u64 v[142:143], v[176:177], 0, s[30:31]
	v_or_b32_e32 v178, 16, v144
	v_lshl_add_u64 v[228:229], v[142:143], 0, s[100:101]
	global_load_dwordx4 v[212:215], v[228:229], off nt
	global_load_dwordx4 v[170:173], v[142:143], off nt
	v_or_b32_e32 v142, s21, v149
	v_ashrrev_i32_e32 v179, 31, v178
	v_ashrrev_i32_e32 v143, 31, v142
	v_lshlrev_b64 v[178:179], 12, v[178:179]
	v_lshlrev_b64 v[146:147], 2, v[142:143]
	v_lshl_add_u64 v[178:179], s[66:67], 0, v[178:179]
	v_lshl_add_u64 v[186:187], v[178:179], 0, v[146:147]
	v_lshl_add_u64 v[178:179], v[174:175], 0, s[12:13]
	v_lshl_add_u64 v[174:175], v[176:177], 0, s[34:35]
	v_lshl_add_u64 v[228:229], v[174:175], 0, s[100:101]
	global_load_dwordx4 v[216:219], v[228:229], off nt
	global_load_dwordx4 v[174:177], v[174:175], off nt
	v_ashrrev_i32_e32 v145, 31, v144
	v_lshlrev_b64 v[180:181], 12, v[144:145]
	v_lshl_add_u64 v[142:143], s[66:67], 0, v[180:181]
	v_lshl_add_u64 v[180:181], v[178:179], 0, s[30:31]
	v_lshl_add_u64 v[182:183], v[178:179], 0, s[34:35]
	v_lshl_add_u64 v[228:229], v[180:181], 0, s[100:101]
	global_load_dwordx4 v[220:223], v[228:229], off nt
	global_load_dwordx4 v[178:181], v[180:181], off nt
	s_nop 0
	v_lshl_add_u64 v[228:229], v[182:183], 0, s[100:101]
	global_load_dwordx4 v[224:227], v[228:229], off nt
	global_load_dwordx4 v[182:185], v[182:183], off nt
	v_lshl_add_u64 v[142:143], v[142:143], 0, v[146:147]
	s_waitcnt vmcnt(0)
	v_lshlrev_b32_e32 v188, 16, v154
	v_and_b32_e32 v189, 0xffff0000, v154
	v_lshlrev_b32_e32 v154, 16, v155
	v_and_b32_e32 v155, 0xffff0000, v155
	v_lshlrev_b32_e32 v190, 16, v156
	v_and_b32_e32 v191, 0xffff0000, v156
	v_lshlrev_b32_e32 v156, 16, v157
	v_and_b32_e32 v157, 0xffff0000, v157
	v_lshlrev_b32_e32 v192, 16, v158
	v_and_b32_e32 v193, 0xffff0000, v158
	v_lshlrev_b32_e32 v158, 16, v159
	v_and_b32_e32 v159, 0xffff0000, v159
	v_pk_add_f32 v[126:127], v[126:127], v[154:155]
	v_pk_add_f32 v[122:123], v[122:123], v[156:157]
	v_lshlrev_b32_e32 v154, 16, v162
	v_and_b32_e32 v155, 0xffff0000, v162
	v_lshlrev_b32_e32 v156, 16, v163
	v_and_b32_e32 v157, 0xffff0000, v163
	v_lshlrev_b32_e32 v162, 16, v164
	v_and_b32_e32 v163, 0xffff0000, v164
	v_lshlrev_b32_e32 v164, 16, v165
	v_and_b32_e32 v165, 0xffff0000, v165
	v_lshlrev_b32_e32 v194, 16, v160
	v_and_b32_e32 v195, 0xffff0000, v160
	v_lshlrev_b32_e32 v160, 16, v161
	v_and_b32_e32 v161, 0xffff0000, v161
	v_pk_add_f32 v[124:125], v[124:125], v[188:189]
	v_pk_add_f32 v[118:119], v[118:119], v[158:159]
	v_pk_add_f32 v[116:117], v[116:117], v[192:193]
	v_pk_add_f32 v[106:107], v[106:107], v[164:165]
	v_pk_add_f32 v[104:105], v[104:105], v[162:163]
	v_pk_add_f32 v[120:121], v[120:121], v[190:191]
	v_pk_add_f32 v[114:115], v[114:115], v[160:161]
	v_pk_add_f32 v[112:113], v[112:113], v[194:195]
	global_store_dwordx4 v[142:143], v[124:127], off
	global_store_dwordx4 v[142:143], v[120:123], off offset:16
	v_pk_add_f32 v[110:111], v[110:111], v[156:157]
	v_pk_add_f32 v[108:109], v[108:109], v[154:155]
	global_store_dwordx4 v[186:187], v[116:119], off
	global_store_dwordx4 v[186:187], v[112:115], off offset:16
	global_store_dwordx4 v[142:143], v[108:111], off offset:512
	global_store_dwordx4 v[142:143], v[104:107], off offset:528
	s_nop 0
	v_lshlrev_b32_e32 v108, 16, v168
	v_lshlrev_b32_e32 v104, 16, v166
	v_and_b32_e32 v105, 0xffff0000, v166
	v_lshlrev_b32_e32 v106, 16, v167
	v_and_b32_e32 v107, 0xffff0000, v167
	v_and_b32_e32 v109, 0xffff0000, v168
	v_lshlrev_b32_e32 v110, 16, v169
	v_and_b32_e32 v111, 0xffff0000, v169
	v_pk_add_f32 v[102:103], v[102:103], v[106:107]
	v_pk_add_f32 v[100:101], v[100:101], v[104:105]
	global_store_dwordx4 v[186:187], v[100:103], off offset:512
	v_pk_add_f32 v[94:95], v[94:95], v[110:111]
	v_pk_add_f32 v[92:93], v[92:93], v[108:109]
	v_or_b32_e32 v100, 32, v144
	global_store_dwordx4 v[186:187], v[92:95], off offset:528
	v_ashrrev_i32_e32 v101, 31, v100
	v_lshlrev_b32_e32 v102, 16, v172
	v_lshlrev_b32_e32 v92, 16, v170
	v_and_b32_e32 v93, 0xffff0000, v170
	v_pk_add_f32 v[92:93], v[96:97], v[92:93]
	v_lshlrev_b64 v[96:97], 12, v[100:101]
; __host__ __device__ __forceinline__ size_t blk_off(int row, int col, int K) { return ((size_t)(row >> 8) * (K >> 6) + (col >> 6)) * (256 * 64) + (size_t)(row & 255) * 64 + (col & 63); }
;     __device__ __forceinline__ void operator()(const f32x4 (&acc)[2][2][4][2], const Unit& u, int wr, int wc, int fr, int fq) const {
;     ...
;                 for (int bj = 0; bj < 2; ++bj) xw[m][bj] = __builtin_nontemporal_load((const u32x4*)(x1b + blk_off(row0 + ai * HALF + m * 16, col0 + bj * HALF, 1024)));
;             asm volatile("" ::: "memory");
; #pragma unroll
;             for (int m = 0; m < 4; ++m) { const size_t off = (size_t)(row0 + ai * HALF + m * 16) * 1024 + col0;
; #pragma unroll
;                 for (int bj = 0; bj < 2; ++bj) {
;                     const u32x4 w = xw[m][bj];
;                     const f32x4 x0 = (f32x4){__builtin_bit_cast(float, w.x << 16), __builtin_bit_cast(float, w.x & 0xffff0000u), __builtin_bit_cast(float, w.y << 16), __builtin_bit_cast(float, w.y & 0xffff0000u)};
;                     const f32x4 x1 = (f32x4){__builtin_bit_cast(float, w.z << 16), __builtin_bit_cast(float, w.z & 0xffff0000u), __builtin_bit_cast(float, w.w << 16), __builtin_bit_cast(float, w.w & 0xffff0000u)};
;                     *(f32x4*)(out + off + bj * HALF) = x0 + acc[ai][bj][m][0]; *(f32x4*)(out + off + bj * HALF + 4) = x1 + acc[ai][bj][m][1]; } }
	v_and_b32_e32 v103, 0xffff0000, v172
	v_lshlrev_b32_e32 v104, 16, v173
	v_and_b32_e32 v105, 0xffff0000, v173
	v_lshl_add_u64 v[96:97], s[66:67], 0, v[96:97]
	v_lshlrev_b32_e32 v94, 16, v171
	v_and_b32_e32 v95, 0xffff0000, v171
	v_lshl_add_u64 v[96:97], v[96:97], 0, v[146:147]
	v_pk_add_f32 v[90:91], v[90:91], v[104:105]
	v_pk_add_f32 v[88:89], v[88:89], v[102:103]
	v_pk_add_f32 v[94:95], v[98:99], v[94:95]
	global_store_dwordx4 v[96:97], v[88:91], off offset:16
	global_store_dwordx4 v[96:97], v[92:95], off
	s_nop 0
	v_lshlrev_b32_e32 v88, 16, v174
	v_and_b32_e32 v89, 0xffff0000, v174
	v_lshlrev_b32_e32 v90, 16, v175
	v_and_b32_e32 v91, 0xffff0000, v175
	v_lshlrev_b32_e32 v92, 16, v176
	v_and_b32_e32 v93, 0xffff0000, v176
	v_lshlrev_b32_e32 v94, 16, v177
	v_and_b32_e32 v95, 0xffff0000, v177
	v_pk_add_f32 v[86:87], v[86:87], v[90:91]
	v_pk_add_f32 v[84:85], v[84:85], v[88:89]
	global_store_dwordx4 v[96:97], v[84:87], off offset:512
	v_pk_add_f32 v[78:79], v[78:79], v[94:95]
	v_pk_add_f32 v[76:77], v[76:77], v[92:93]
	v_or_b32_e32 v84, 48, v144
	global_store_dwordx4 v[96:97], v[76:79], off offset:528
	v_ashrrev_i32_e32 v85, 31, v84
	v_add_u32_e32 v96, 0x80, v144
	v_lshlrev_b32_e32 v76, 16, v178
	v_and_b32_e32 v77, 0xffff0000, v178
	v_pk_add_f32 v[76:77], v[80:81], v[76:77]
	v_lshlrev_b64 v[80:81], 12, v[84:85]
	v_lshlrev_b32_e32 v78, 16, v179
	v_and_b32_e32 v79, 0xffff0000, v179
	v_lshl_add_u64 v[80:81], s[66:67], 0, v[80:81]
	v_pk_add_f32 v[78:79], v[82:83], v[78:79]
	v_lshl_add_u64 v[80:81], v[80:81], 0, v[146:147]
	global_store_dwordx4 v[80:81], v[76:79], off
	v_lshlrev_b32_e32 v86, 16, v180
	v_and_b32_e32 v87, 0xffff0000, v180
	v_lshlrev_b32_e32 v76, 16, v184
	v_and_b32_e32 v77, 0xffff0000, v184
	v_lshlrev_b32_e32 v78, 16, v185
	v_and_b32_e32 v79, 0xffff0000, v185
	v_pk_add_f32 v[66:67], v[66:67], v[78:79]
	v_pk_add_f32 v[64:65], v[64:65], v[76:77]
	global_store_dwordx4 v[80:81], v[64:67], off offset:528
	v_lshlrev_b32_e32 v88, 16, v181
	v_and_b32_e32 v89, 0xffff0000, v181
	v_ashrrev_i32_e32 v64, 8, v96
	v_ashrrev_i32_e32 v65, 31, v64
	v_pk_add_f32 v[74:75], v[74:75], v[88:89]
	v_pk_add_f32 v[72:73], v[72:73], v[86:87]
	v_lshlrev_b64 v[64:65], 19, v[64:65]
	global_store_dwordx4 v[80:81], v[72:75], off offset:16
	v_lshl_add_u64 v[64:65], s[10:11], 0, v[64:65]
	v_lshlrev_b32_e32 v66, 7, v96
	v_lshlrev_b32_e32 v72, 16, v182
	v_and_b32_e32 v73, 0xffff0000, v182
	v_lshlrev_b32_e32 v74, 16, v183
	v_and_b32_e32 v75, 0xffff0000, v183
	v_pk_add_f32 v[70:71], v[70:71], v[74:75]
	v_pk_add_f32 v[68:69], v[68:69], v[72:73]
	v_lshl_add_u64 v[64:65], v[64:65], 0, v[136:137]
	v_and_b32_e32 v136, 0x6780, v66
	global_store_dwordx4 v[80:81], v[68:71], off offset:512
	v_lshl_add_u64 v[64:65], v[64:65], 0, v[136:137]
	v_lshl_add_u64 v[66:67], v[64:65], 0, s[30:31]
	v_lshl_add_u64 v[80:81], v[64:65], 0, s[34:35]
	s_nop 0
	v_lshl_add_u64 v[66:67], v[64:65], 0, s[8:9]
	v_lshl_add_u64 v[84:85], v[66:67], 0, s[30:31]
	v_lshl_add_u64 v[66:67], v[66:67], 0, s[34:35]
	v_lshl_add_u64 v[64:65], v[64:65], 0, s[12:13]
	v_lshl_add_u64 v[66:67], v[64:65], 0, s[30:31]
	v_lshl_add_u64 v[64:65], v[64:65], 0, s[34:35]
	s_nop 0
	v_ashrrev_i32_e32 v97, 31, v96
	v_lshlrev_b32_e32 v98, 16, v196
	v_and_b32_e32 v99, 0xffff0000, v196
	v_lshlrev_b32_e32 v68, 16, v197
	v_and_b32_e32 v69, 0xffff0000, v197
	v_pk_add_f32 v[62:63], v[62:63], v[68:69]
	v_lshlrev_b64 v[68:69], 12, v[96:97]
	v_lshl_add_u64 v[68:69], s[66:67], 0, v[68:69]
	v_pk_add_f32 v[60:61], v[60:61], v[98:99]
	v_lshl_add_u64 v[68:69], v[68:69], 0, v[146:147]
	global_store_dwordx4 v[68:69], v[60:63], off
	v_lshlrev_b32_e32 v100, 16, v198
	v_and_b32_e32 v101, 0xffff0000, v198
	v_lshlrev_b32_e32 v60, 16, v202
	v_and_b32_e32 v61, 0xffff0000, v202
	v_lshlrev_b32_e32 v62, 16, v203
	v_and_b32_e32 v63, 0xffff0000, v203
	v_lshlrev_b32_e32 v70, 16, v199
	v_and_b32_e32 v71, 0xffff0000, v199
	v_pk_add_f32 v[46:47], v[46:47], v[62:63]
	v_pk_add_f32 v[44:45], v[44:45], v[60:61]
	v_pk_add_f32 v[58:59], v[58:59], v[70:71]
	v_pk_add_f32 v[56:57], v[56:57], v[100:101]
	global_store_dwordx4 v[68:69], v[44:47], off offset:528
	global_store_dwordx4 v[68:69], v[56:59], off offset:16
	s_nop 0
; #define PG8_BAR __builtin_amdgcn_s_barrier()
;     __device__ __forceinline__ void operator()(const f32x4 (&acc)[2][2][4][2], const Unit& u, int wr, int wc, int fr, int fq) const {
;     ...
;             for (int m = 0; m < 4; ++m) { const size_t off = (size_t)(row0 + ai * HALF + m * 16) * 1024 + col0;
; #pragma unroll
;                 for (int bj = 0; bj < 2; ++bj) {
;                     const u32x4 w = xw[m][bj];
;                     const f32x4 x0 = (f32x4){__builtin_bit_cast(float, w.x << 16), __builtin_bit_cast(float, w.x & 0xffff0000u), __builtin_bit_cast(float, w.y << 16), __builtin_bit_cast(float, w.y & 0xffff0000u)};
;                     const f32x4 x1 = (f32x4){__builtin_bit_cast(float, w.z << 16), __builtin_bit_cast(float, w.z & 0xffff0000u), __builtin_bit_cast(float, w.w << 16), __builtin_bit_cast(float, w.w & 0xffff0000u)};
;                     *(f32x4*)(out + off + bj * HALF) = x0 + acc[ai][bj][m][0]; *(f32x4*)(out + off + bj * HALF + 4) = x1 + acc[ai][bj][m][1]; } }
; template <class Epi, class Sched, bool ALIGN_EPI = false, bool SP2 = false, bool ABLK = false>
; __device__ __forceinline__ void gemm_phase(PG8_LAS unsigned char* lds, const Gemm g, const Sched& S, const Epi& E) {
;     ...
;         if (!has_next) break;
; #pragma unroll
;         for (int a = 0; a < 2; ++a)
; #pragma unroll
;             for (int b = 0; b < 2; ++b)
; #pragma unroll
;                 for (int m = 0; m < 4; ++m)
; #pragma unroll
;                     for (int n = 0; n < 2; ++n) acc[a][b][m][n] = (f32x4){0.f, 0.f, 0.f, 0.f};
;         cur = nxt; cA = nA; cB = nB; ++ui;
;         if constexpr (ALIGN_EPI) { if (wr == 1) PG8_BAR; }
	v_lshlrev_b32_e32 v46, 16, v205
	v_and_b32_e32 v47, 0xffff0000, v205
	v_lshlrev_b32_e32 v56, 16, v200
	v_and_b32_e32 v57, 0xffff0000, v200
	v_lshlrev_b32_e32 v58, 16, v201
	v_and_b32_e32 v59, 0xffff0000, v201
	v_lshlrev_b32_e32 v44, 16, v204
	v_and_b32_e32 v45, 0xffff0000, v204
	v_pk_add_f32 v[46:47], v[50:51], v[46:47]
	v_add_co_u32_e32 v50, vcc, s58, v142
	v_pk_add_f32 v[54:55], v[54:55], v[58:59]
	v_pk_add_f32 v[52:53], v[52:53], v[56:57]
	v_pk_add_f32 v[44:45], v[48:49], v[44:45]
	v_addc_co_u32_e32 v51, vcc, 0, v143, vcc
	global_store_dwordx4 v[68:69], v[52:55], off offset:512
	global_store_dwordx4 v[50:51], v[44:47], off
	v_lshl_add_u64 v[48:49], v[142:143], 0, s[14:15]
	v_lshlrev_b32_e32 v52, 16, v206
	v_and_b32_e32 v53, 0xffff0000, v206
	v_lshlrev_b32_e32 v54, 16, v207
	v_and_b32_e32 v55, 0xffff0000, v207
	v_lshlrev_b32_e32 v44, 16, v210
	v_and_b32_e32 v45, 0xffff0000, v210
	v_lshlrev_b32_e32 v46, 16, v211
	v_and_b32_e32 v47, 0xffff0000, v211
	v_pk_add_f32 v[42:43], v[42:43], v[54:55]
	v_pk_add_f32 v[40:41], v[40:41], v[52:53]
	v_pk_add_f32 v[30:31], v[30:31], v[46:47]
	v_pk_add_f32 v[28:29], v[28:29], v[44:45]
	global_store_dwordx4 v[48:49], v[40:43], off offset:16
	global_store_dwordx4 v[48:49], v[28:31], off offset:528
	s_nop 0
	v_lshlrev_b32_e32 v40, 16, v208
	v_and_b32_e32 v41, 0xffff0000, v208
	v_lshlrev_b32_e32 v42, 16, v209
	v_and_b32_e32 v43, 0xffff0000, v209
	v_lshlrev_b32_e32 v30, 16, v213
	v_and_b32_e32 v31, 0xffff0000, v213
	v_pk_add_f32 v[38:39], v[38:39], v[42:43]
	v_pk_add_f32 v[36:37], v[36:37], v[40:41]
	v_lshlrev_b32_e32 v28, 16, v212
	v_and_b32_e32 v29, 0xffff0000, v212
	v_pk_add_f32 v[30:31], v[34:35], v[30:31]
	v_add_co_u32_e32 v34, vcc, s59, v142
	global_store_dwordx4 v[48:49], v[36:39], off offset:512
	v_pk_add_f32 v[28:29], v[32:33], v[28:29]
	v_addc_co_u32_e32 v35, vcc, 0, v143, vcc
	v_lshlrev_b32_e32 v36, 16, v214
	v_and_b32_e32 v37, 0xffff0000, v214
	v_lshlrev_b32_e32 v38, 16, v215
	v_and_b32_e32 v39, 0xffff0000, v215
	v_lshl_add_u64 v[32:33], v[142:143], 0, s[16:17]
	global_store_dwordx4 v[34:35], v[28:31], off
	v_pk_add_f32 v[26:27], v[26:27], v[38:39]
	v_pk_add_f32 v[24:25], v[24:25], v[36:37]
	v_lshlrev_b32_e32 v28, 16, v218
	v_and_b32_e32 v29, 0xffff0000, v218
	v_lshlrev_b32_e32 v30, 16, v219
	v_and_b32_e32 v31, 0xffff0000, v219
	global_store_dwordx4 v[32:33], v[24:27], off offset:16
	v_pk_add_f32 v[14:15], v[14:15], v[30:31]
	v_pk_add_f32 v[12:13], v[12:13], v[28:29]
	v_lshlrev_b32_e32 v24, 16, v216
	v_and_b32_e32 v25, 0xffff0000, v216
	v_lshlrev_b32_e32 v26, 16, v217
	v_and_b32_e32 v27, 0xffff0000, v217
	v_pk_add_f32 v[22:23], v[22:23], v[26:27]
	v_pk_add_f32 v[20:21], v[20:21], v[24:25]
	global_store_dwordx4 v[32:33], v[12:15], off offset:528
	global_store_dwordx4 v[32:33], v[20:23], off offset:512
	s_nop 0
	v_lshlrev_b32_e32 v14, 16, v221
	v_and_b32_e32 v15, 0xffff0000, v221
	v_lshlrev_b32_e32 v12, 16, v220
	v_and_b32_e32 v13, 0xffff0000, v220
	v_lshlrev_b32_e32 v20, 16, v222
	v_and_b32_e32 v21, 0xffff0000, v222
	v_lshlrev_b32_e32 v22, 16, v223
	v_and_b32_e32 v23, 0xffff0000, v223
	v_pk_add_f32 v[14:15], v[18:19], v[14:15]
	v_add_co_u32_e32 v18, vcc, s60, v142
	v_pk_add_f32 v[12:13], v[16:17], v[12:13]
	v_lshl_add_u64 v[16:17], v[142:143], 0, s[18:19]
	v_addc_co_u32_e32 v19, vcc, 0, v143, vcc
	v_pk_add_f32 v[10:11], v[10:11], v[22:23]
	v_pk_add_f32 v[8:9], v[8:9], v[20:21]
	global_store_dwordx4 v[18:19], v[12:15], off
	global_store_dwordx4 v[16:17], v[8:11], off offset:16
	s_andn2_b64 vcc, exec, s[26:27]
	v_lshlrev_b32_e32 v12, 16, v226
	v_lshlrev_b32_e32 v8, 16, v224
	v_and_b32_e32 v9, 0xffff0000, v224
	v_lshlrev_b32_e32 v10, 16, v225
	v_and_b32_e32 v11, 0xffff0000, v225
	v_and_b32_e32 v13, 0xffff0000, v226
	v_lshlrev_b32_e32 v14, 16, v227
	v_and_b32_e32 v15, 0xffff0000, v227
	v_pk_add_f32 v[6:7], v[6:7], v[10:11]
	v_pk_add_f32 v[4:5], v[4:5], v[8:9]
	v_pk_add_f32 v[2:3], v[2:3], v[14:15]
	v_pk_add_f32 v[0:1], v[0:1], v[12:13]
	global_store_dwordx4 v[16:17], v[4:7], off offset:512
	global_store_dwordx4 v[16:17], v[0:3], off offset:528
	s_mov_b64 s[26:27], -1
	s_cbranch_vccnz .LBB0_574
	s_andn2_b64 vcc, exec, s[2:3]
	s_cbranch_vccnz .LBB0_573
	s_barrier
	s_branch .LBB0_573
